# select passes: loop counter and exit test computed in front of the stage barrier
# baseline (speedup 1.0000x reference)
.Lp1_noprio:
	s_mov_b32 s0, 0
	ds_read_b128 v[176:179], v99 offset:0
	ds_read_b128 v[180:183], v99 offset:4096
	ds_read_b128 v[230:233], v99 offset:1024
	ds_read_b128 v[234:237], v99 offset:5120
	ds_read_b128 v[238:241], v99 offset:2048
	ds_read_b128 v[242:245], v99 offset:6144
	ds_read_b128 v[246:249], v99 offset:3072
	ds_read_b128 v[50:53], v99 offset:7168
	s_waitcnt lgkmcnt(7)
	v_mfma_f32_32x32x16_bf16 v[0:15], v[34:37], v[176:179], 0
	s_waitcnt lgkmcnt(6)
	v_mfma_f32_32x32x16_bf16 v[160:175], v[34:37], v[180:183], 0
	s_waitcnt vmcnt(3)
	ds_write_b128 v140, v[16:19] offset:8192
	s_add_i32 s1, s0, 5
	s_min_i32 s1, s1, s14
	v_mad_i64_i32 v[184:185], s[2:3], s1, v193, v[116:117]
	global_load_dwordx4 v[16:19], v[184:185], off
	s_waitcnt lgkmcnt(6)
	v_mfma_f32_32x32x16_bf16 v[0:15], v[38:41], v[230:233], v[0:15]
	s_waitcnt lgkmcnt(5)
	v_mfma_f32_32x32x16_bf16 v[160:175], v[38:41], v[234:237], v[160:175]
	s_waitcnt lgkmcnt(4)
	v_mfma_f32_32x32x16_bf16 v[0:15], v[42:45], v[238:241], v[0:15]
	s_waitcnt lgkmcnt(3)
	v_mfma_f32_32x32x16_bf16 v[160:175], v[42:45], v[242:245], v[160:175]
	s_waitcnt lgkmcnt(2)
	v_mfma_f32_32x32x16_bf16 v[0:15], v[46:49], v[246:249], v[0:15]
	s_waitcnt lgkmcnt(1)
	v_mfma_f32_32x32x16_bf16 v[160:175], v[46:49], v[50:53], v[160:175]
	s_add_u32 s0, s0, 1
	s_cmp_ge_u32 s0, s13
	s_waitcnt lgkmcnt(0)
	s_barrier
	s_cbranch_scc1 .Lp1_drain0
.Lp1_c1:
	ds_read_b128 v[176:179], v99 offset:8192
	ds_read_b128 v[180:183], v99 offset:12288
	ds_read_b128 v[230:233], v99 offset:9216
	ds_read_b128 v[234:237], v99 offset:13312
	ds_read_b128 v[238:241], v99 offset:10240
	ds_read_b128 v[242:245], v99 offset:14336
	ds_read_b128 v[246:249], v99 offset:11264
	ds_read_b128 v[50:53], v99 offset:15360
	v_max_i32_e32 v56, 0, v8
	v_max_i32_e32 v57, 0, v0
	v_max_i32_e32 v60, 0, v9
	v_max_i32_e32 v61, 0, v1
	v_max_i32_e32 v64, 0, v10
	v_max_i32_e32 v65, 0, v2
	v_max_i32_e32 v154, 0, v11
	v_max_i32_e32 v155, 0, v3
	v_mul_f32_e32 v156, v100, v56
	v_mul_f32_e32 v157, v101, v57
	s_waitcnt lgkmcnt(7)
	v_mfma_f32_32x32x16_bf16 v[198:213], v[34:37], v[176:179], 0
	v_fmac_f32_e32 v156, v102, v60
	v_fmac_f32_e32 v157, v103, v61
	v_fmac_f32_e32 v156, v104, v64
	v_fmac_f32_e32 v157, v105, v65
	v_fmac_f32_e32 v156, v106, v154
	v_fmac_f32_e32 v157, v107, v155
	v_max_i32_e32 v56, 0, v12
	v_max_i32_e32 v57, 0, v4
	v_max_i32_e32 v60, 0, v13
	v_max_i32_e32 v61, 0, v5
	v_max_i32_e32 v64, 0, v14
	s_waitcnt lgkmcnt(6)
	v_mfma_f32_32x32x16_bf16 v[214:229], v[34:37], v[180:183], 0
	s_waitcnt vmcnt(3)
	ds_write_b128 v140, v[20:23]
	s_add_i32 s1, s0, 5
	s_min_i32 s1, s1, s14
	v_mad_i64_i32 v[184:185], s[2:3], s1, v193, v[116:117]
	global_load_dwordx4 v[20:23], v[184:185], off
	v_max_i32_e32 v65, 0, v6
	v_max_i32_e32 v154, 0, v15
	v_max_i32_e32 v155, 0, v7
	v_fmac_f32_e32 v156, v108, v56
	v_fmac_f32_e32 v157, v109, v57
	v_fmac_f32_e32 v156, v110, v60
	v_fmac_f32_e32 v157, v111, v61
	v_fmac_f32_e32 v156, v112, v64
	v_fmac_f32_e32 v157, v113, v65
	v_fmac_f32_e32 v156, v114, v154
	v_fmac_f32_e32 v157, v115, v155
	s_waitcnt lgkmcnt(6)
	v_mfma_f32_32x32x16_bf16 v[198:213], v[38:41], v[230:233], v[198:213]
	v_bfe_u32 v56, v157, 19, 12
	v_bfe_u32 v64, v156, 19, 12
	v_med3_u32 v56, v56, s94, v194
	v_med3_u32 v64, v64, s94, v194
	v_sub_u32_e32 v57, 0x86f, v56
	v_add_u32_e32 v60, 0xfffffb90, v56
	v_sub_u32_e32 v65, 0x86f, v64
	v_add_u32_e32 v154, 0xfffffb90, v64
	v_cmp_gt_f32_e32 vcc, 0, v157
	s_nop 1
	v_cndmask_b32_e32 v56, v60, v57, vcc
	s_waitcnt lgkmcnt(5)
	v_mfma_f32_32x32x16_bf16 v[214:229], v[38:41], v[234:237], v[214:229]
	v_cmp_gt_f32_e32 vcc, 0, v156
	v_lshl_add_u32 v61, v56, 2, v33
	ds_add_u32 v61, v188
	v_cndmask_b32_e32 v64, v154, v65, vcc
	v_lshl_add_u32 v155, v64, 2, v33
	ds_add_u32 v155, v188 offset:4096
	v_max_i32_e32 v56, 0, v168
	v_max_i32_e32 v57, 0, v160
	v_max_i32_e32 v60, 0, v169
	v_max_i32_e32 v61, 0, v161
	v_max_i32_e32 v64, 0, v170
	s_waitcnt lgkmcnt(6)
	v_mfma_f32_32x32x16_bf16 v[198:213], v[42:45], v[238:241], v[198:213]
	v_max_i32_e32 v65, 0, v162
	v_max_i32_e32 v154, 0, v171
	v_max_i32_e32 v155, 0, v163
	v_mul_f32_e32 v156, v100, v56
	v_mul_f32_e32 v157, v101, v57
	v_fmac_f32_e32 v156, v102, v60
	v_fmac_f32_e32 v157, v103, v61
	v_fmac_f32_e32 v156, v104, v64
	v_fmac_f32_e32 v157, v105, v65
	v_fmac_f32_e32 v156, v106, v154
	v_fmac_f32_e32 v157, v107, v155
	s_waitcnt lgkmcnt(5)
	v_mfma_f32_32x32x16_bf16 v[214:229], v[42:45], v[242:245], v[214:229]
	v_max_i32_e32 v56, 0, v172
	v_max_i32_e32 v57, 0, v164
	v_max_i32_e32 v60, 0, v173
	v_max_i32_e32 v61, 0, v165
	v_max_i32_e32 v64, 0, v174
	v_max_i32_e32 v65, 0, v166
	v_max_i32_e32 v154, 0, v175
	v_max_i32_e32 v155, 0, v167
	v_fmac_f32_e32 v156, v108, v56
	v_fmac_f32_e32 v157, v109, v57
	v_fmac_f32_e32 v156, v110, v60
	s_waitcnt lgkmcnt(4)
	v_mfma_f32_32x32x16_bf16 v[198:213], v[46:49], v[246:249], v[198:213]
	v_fmac_f32_e32 v157, v111, v61
	v_fmac_f32_e32 v156, v112, v64
	v_fmac_f32_e32 v157, v113, v65
	v_fmac_f32_e32 v156, v114, v154
	v_fmac_f32_e32 v157, v115, v155
	v_bfe_u32 v56, v157, 19, 12
	v_bfe_u32 v64, v156, 19, 12
	v_med3_u32 v56, v56, s94, v194
	v_med3_u32 v64, v64, s94, v194
	v_sub_u32_e32 v57, 0x86f, v56
	v_add_u32_e32 v60, 0xfffffb90, v56
	s_waitcnt lgkmcnt(3)
	v_mfma_f32_32x32x16_bf16 v[214:229], v[46:49], v[50:53], v[214:229]
	v_sub_u32_e32 v65, 0x86f, v64
	v_add_u32_e32 v154, 0xfffffb90, v64
	v_cmp_gt_f32_e32 vcc, 0, v157
	s_nop 1
	v_cndmask_b32_e32 v56, v60, v57, vcc
	v_cmp_gt_f32_e32 vcc, 0, v156
	v_lshl_add_u32 v61, v56, 2, v33
	ds_add_u32 v61, v188
	v_cndmask_b32_e32 v64, v154, v65, vcc
	v_lshl_add_u32 v155, v64, 2, v33
	ds_add_u32 v155, v188 offset:4096
	s_add_u32 s0, s0, 1
	s_cmp_ge_u32 s0, s13
	s_waitcnt lgkmcnt(4)
	s_barrier
	s_cbranch_scc1 .Lp1_drain1
.Lp1_c2:
	ds_read_b128 v[176:179], v99 offset:0
	ds_read_b128 v[180:183], v99 offset:4096
	ds_read_b128 v[230:233], v99 offset:1024
	ds_read_b128 v[234:237], v99 offset:5120
	ds_read_b128 v[238:241], v99 offset:2048
	ds_read_b128 v[242:245], v99 offset:6144
	ds_read_b128 v[246:249], v99 offset:3072
	ds_read_b128 v[50:53], v99 offset:7168
	v_max_i32_e32 v56, 0, v206
	v_max_i32_e32 v57, 0, v198
	v_max_i32_e32 v60, 0, v207
	v_max_i32_e32 v61, 0, v199
	v_max_i32_e32 v64, 0, v208
	v_max_i32_e32 v65, 0, v200
	v_max_i32_e32 v154, 0, v209
	v_max_i32_e32 v155, 0, v201
	v_mul_f32_e32 v156, v100, v56
	v_mul_f32_e32 v157, v101, v57
	s_waitcnt lgkmcnt(7)
	v_mfma_f32_32x32x16_bf16 v[0:15], v[34:37], v[176:179], 0
	v_fmac_f32_e32 v156, v102, v60
	v_fmac_f32_e32 v157, v103, v61
	v_fmac_f32_e32 v156, v104, v64
	v_fmac_f32_e32 v157, v105, v65
	v_fmac_f32_e32 v156, v106, v154
	v_fmac_f32_e32 v157, v107, v155
	v_max_i32_e32 v56, 0, v210
	v_max_i32_e32 v57, 0, v202
	v_max_i32_e32 v60, 0, v211
	v_max_i32_e32 v61, 0, v203
	v_max_i32_e32 v64, 0, v212
	s_waitcnt lgkmcnt(6)
	v_mfma_f32_32x32x16_bf16 v[160:175], v[34:37], v[180:183], 0
	s_waitcnt vmcnt(3)
	ds_write_b128 v140, v[24:27] offset:8192
	s_add_i32 s1, s0, 5
	s_min_i32 s1, s1, s14
	v_mad_i64_i32 v[184:185], s[2:3], s1, v193, v[116:117]
	global_load_dwordx4 v[24:27], v[184:185], off
	v_max_i32_e32 v65, 0, v204
	v_max_i32_e32 v154, 0, v213
	v_max_i32_e32 v155, 0, v205
	v_fmac_f32_e32 v156, v108, v56
	v_fmac_f32_e32 v157, v109, v57
	v_fmac_f32_e32 v156, v110, v60
	v_fmac_f32_e32 v157, v111, v61
	v_fmac_f32_e32 v156, v112, v64
	v_fmac_f32_e32 v157, v113, v65
	v_fmac_f32_e32 v156, v114, v154
	v_fmac_f32_e32 v157, v115, v155
	s_waitcnt lgkmcnt(6)
	v_mfma_f32_32x32x16_bf16 v[0:15], v[38:41], v[230:233], v[0:15]
	v_bfe_u32 v56, v157, 19, 12
	v_bfe_u32 v64, v156, 19, 12
	v_med3_u32 v56, v56, s94, v194
	v_med3_u32 v64, v64, s94, v194
	v_sub_u32_e32 v57, 0x86f, v56
	v_add_u32_e32 v60, 0xfffffb90, v56
	v_sub_u32_e32 v65, 0x86f, v64
	v_add_u32_e32 v154, 0xfffffb90, v64
	v_cmp_gt_f32_e32 vcc, 0, v157
	s_nop 1
	v_cndmask_b32_e32 v56, v60, v57, vcc
	s_waitcnt lgkmcnt(5)
	v_mfma_f32_32x32x16_bf16 v[160:175], v[38:41], v[234:237], v[160:175]
	v_cmp_gt_f32_e32 vcc, 0, v156
	v_lshl_add_u32 v61, v56, 2, v33
	ds_add_u32 v61, v188
	v_cndmask_b32_e32 v64, v154, v65, vcc
	v_lshl_add_u32 v155, v64, 2, v33
	ds_add_u32 v155, v188 offset:4096
	v_max_i32_e32 v56, 0, v222
	v_max_i32_e32 v57, 0, v214
	v_max_i32_e32 v60, 0, v223
	v_max_i32_e32 v61, 0, v215
	v_max_i32_e32 v64, 0, v224
	s_waitcnt lgkmcnt(6)
	v_mfma_f32_32x32x16_bf16 v[0:15], v[42:45], v[238:241], v[0:15]
	v_max_i32_e32 v65, 0, v216
	v_max_i32_e32 v154, 0, v225
	v_max_i32_e32 v155, 0, v217
	v_mul_f32_e32 v156, v100, v56
	v_mul_f32_e32 v157, v101, v57
	v_fmac_f32_e32 v156, v102, v60
	v_fmac_f32_e32 v157, v103, v61
	v_fmac_f32_e32 v156, v104, v64
	v_fmac_f32_e32 v157, v105, v65
	v_fmac_f32_e32 v156, v106, v154
	v_fmac_f32_e32 v157, v107, v155
	s_waitcnt lgkmcnt(5)
	v_mfma_f32_32x32x16_bf16 v[160:175], v[42:45], v[242:245], v[160:175]
	v_max_i32_e32 v56, 0, v226
	v_max_i32_e32 v57, 0, v218
	v_max_i32_e32 v60, 0, v227
	v_max_i32_e32 v61, 0, v219
	v_max_i32_e32 v64, 0, v228
	v_max_i32_e32 v65, 0, v220
	v_max_i32_e32 v154, 0, v229
	v_max_i32_e32 v155, 0, v221
	v_fmac_f32_e32 v156, v108, v56
	v_fmac_f32_e32 v157, v109, v57
	v_fmac_f32_e32 v156, v110, v60
	s_waitcnt lgkmcnt(4)
	v_mfma_f32_32x32x16_bf16 v[0:15], v[46:49], v[246:249], v[0:15]
	v_fmac_f32_e32 v157, v111, v61
	v_fmac_f32_e32 v156, v112, v64
	v_fmac_f32_e32 v157, v113, v65
	v_fmac_f32_e32 v156, v114, v154
	v_fmac_f32_e32 v157, v115, v155
	v_bfe_u32 v56, v157, 19, 12
	v_bfe_u32 v64, v156, 19, 12
	v_med3_u32 v56, v56, s94, v194
	v_med3_u32 v64, v64, s94, v194
	v_sub_u32_e32 v57, 0x86f, v56
	v_add_u32_e32 v60, 0xfffffb90, v56
	s_waitcnt lgkmcnt(3)
	v_mfma_f32_32x32x16_bf16 v[160:175], v[46:49], v[50:53], v[160:175]
	v_sub_u32_e32 v65, 0x86f, v64
	v_add_u32_e32 v154, 0xfffffb90, v64
	v_cmp_gt_f32_e32 vcc, 0, v157
	s_nop 1
	v_cndmask_b32_e32 v56, v60, v57, vcc
	v_cmp_gt_f32_e32 vcc, 0, v156
	v_lshl_add_u32 v61, v56, 2, v33
	ds_add_u32 v61, v188
	v_cndmask_b32_e32 v64, v154, v65, vcc
	v_lshl_add_u32 v155, v64, 2, v33
	ds_add_u32 v155, v188 offset:4096
	s_add_u32 s0, s0, 1
	s_cmp_ge_u32 s0, s13
	s_waitcnt lgkmcnt(4)
	s_barrier
	s_cbranch_scc1 .Lp1_drain0
.Lp1_c3:
	ds_read_b128 v[176:179], v99 offset:8192
	ds_read_b128 v[180:183], v99 offset:12288
	ds_read_b128 v[230:233], v99 offset:9216
	ds_read_b128 v[234:237], v99 offset:13312
	ds_read_b128 v[238:241], v99 offset:10240
	ds_read_b128 v[242:245], v99 offset:14336
	ds_read_b128 v[246:249], v99 offset:11264
	ds_read_b128 v[50:53], v99 offset:15360
	v_max_i32_e32 v56, 0, v8
	v_max_i32_e32 v57, 0, v0
	v_max_i32_e32 v60, 0, v9
	v_max_i32_e32 v61, 0, v1
	v_max_i32_e32 v64, 0, v10
	v_max_i32_e32 v65, 0, v2
	v_max_i32_e32 v154, 0, v11
	v_max_i32_e32 v155, 0, v3
	v_mul_f32_e32 v156, v100, v56
	v_mul_f32_e32 v157, v101, v57
	s_waitcnt lgkmcnt(7)
	v_mfma_f32_32x32x16_bf16 v[198:213], v[34:37], v[176:179], 0
	v_fmac_f32_e32 v156, v102, v60
	v_fmac_f32_e32 v157, v103, v61
	v_fmac_f32_e32 v156, v104, v64
	v_fmac_f32_e32 v157, v105, v65
	v_fmac_f32_e32 v156, v106, v154
	v_fmac_f32_e32 v157, v107, v155
	v_max_i32_e32 v56, 0, v12
	v_max_i32_e32 v57, 0, v4
	v_max_i32_e32 v60, 0, v13
	v_max_i32_e32 v61, 0, v5
	v_max_i32_e32 v64, 0, v14
	s_waitcnt lgkmcnt(6)
	v_mfma_f32_32x32x16_bf16 v[214:229], v[34:37], v[180:183], 0
	s_waitcnt vmcnt(3)
	ds_write_b128 v140, v[28:31]
	s_add_i32 s1, s0, 5
	s_min_i32 s1, s1, s14
	v_mad_i64_i32 v[184:185], s[2:3], s1, v193, v[116:117]
	global_load_dwordx4 v[28:31], v[184:185], off
	v_max_i32_e32 v65, 0, v6
	v_max_i32_e32 v154, 0, v15
	v_max_i32_e32 v155, 0, v7
	v_fmac_f32_e32 v156, v108, v56
	v_fmac_f32_e32 v157, v109, v57
	v_fmac_f32_e32 v156, v110, v60
	v_fmac_f32_e32 v157, v111, v61
	v_fmac_f32_e32 v156, v112, v64
	v_fmac_f32_e32 v157, v113, v65
	v_fmac_f32_e32 v156, v114, v154
	v_fmac_f32_e32 v157, v115, v155
	s_waitcnt lgkmcnt(6)
	v_mfma_f32_32x32x16_bf16 v[198:213], v[38:41], v[230:233], v[198:213]
	v_bfe_u32 v56, v157, 19, 12
	v_bfe_u32 v64, v156, 19, 12
	v_med3_u32 v56, v56, s94, v194
	v_med3_u32 v64, v64, s94, v194
	v_sub_u32_e32 v57, 0x86f, v56
	v_add_u32_e32 v60, 0xfffffb90, v56
	v_sub_u32_e32 v65, 0x86f, v64
	v_add_u32_e32 v154, 0xfffffb90, v64
	v_cmp_gt_f32_e32 vcc, 0, v157
	s_nop 1
	v_cndmask_b32_e32 v56, v60, v57, vcc
	s_waitcnt lgkmcnt(5)
	v_mfma_f32_32x32x16_bf16 v[214:229], v[38:41], v[234:237], v[214:229]
	v_cmp_gt_f32_e32 vcc, 0, v156
	v_lshl_add_u32 v61, v56, 2, v33
	ds_add_u32 v61, v188
	v_cndmask_b32_e32 v64, v154, v65, vcc
	v_lshl_add_u32 v155, v64, 2, v33
	ds_add_u32 v155, v188 offset:4096
	v_max_i32_e32 v56, 0, v168
	v_max_i32_e32 v57, 0, v160
	v_max_i32_e32 v60, 0, v169
	v_max_i32_e32 v61, 0, v161
	v_max_i32_e32 v64, 0, v170
	s_waitcnt lgkmcnt(6)
	v_mfma_f32_32x32x16_bf16 v[198:213], v[42:45], v[238:241], v[198:213]
	v_max_i32_e32 v65, 0, v162
	v_max_i32_e32 v154, 0, v171
	v_max_i32_e32 v155, 0, v163
	v_mul_f32_e32 v156, v100, v56
	v_mul_f32_e32 v157, v101, v57
	v_fmac_f32_e32 v156, v102, v60
	v_fmac_f32_e32 v157, v103, v61
	v_fmac_f32_e32 v156, v104, v64
	v_fmac_f32_e32 v157, v105, v65
	v_fmac_f32_e32 v156, v106, v154
	v_fmac_f32_e32 v157, v107, v155
	s_waitcnt lgkmcnt(5)
	v_mfma_f32_32x32x16_bf16 v[214:229], v[42:45], v[242:245], v[214:229]
	v_max_i32_e32 v56, 0, v172
	v_max_i32_e32 v57, 0, v164
	v_max_i32_e32 v60, 0, v173
	v_max_i32_e32 v61, 0, v165
	v_max_i32_e32 v64, 0, v174
	v_max_i32_e32 v65, 0, v166
	v_max_i32_e32 v154, 0, v175
	v_max_i32_e32 v155, 0, v167
	v_fmac_f32_e32 v156, v108, v56
	v_fmac_f32_e32 v157, v109, v57
	v_fmac_f32_e32 v156, v110, v60
	s_waitcnt lgkmcnt(4)
	v_mfma_f32_32x32x16_bf16 v[198:213], v[46:49], v[246:249], v[198:213]
	v_fmac_f32_e32 v157, v111, v61
	v_fmac_f32_e32 v156, v112, v64
	v_fmac_f32_e32 v157, v113, v65
	v_fmac_f32_e32 v156, v114, v154
	v_fmac_f32_e32 v157, v115, v155
	v_bfe_u32 v56, v157, 19, 12
	v_bfe_u32 v64, v156, 19, 12
	v_med3_u32 v56, v56, s94, v194
	v_med3_u32 v64, v64, s94, v194
	v_sub_u32_e32 v57, 0x86f, v56
	v_add_u32_e32 v60, 0xfffffb90, v56
	s_waitcnt lgkmcnt(3)
	v_mfma_f32_32x32x16_bf16 v[214:229], v[46:49], v[50:53], v[214:229]
	v_sub_u32_e32 v65, 0x86f, v64
	v_add_u32_e32 v154, 0xfffffb90, v64
	v_cmp_gt_f32_e32 vcc, 0, v157
	s_nop 1
	v_cndmask_b32_e32 v56, v60, v57, vcc
	v_cmp_gt_f32_e32 vcc, 0, v156
	v_lshl_add_u32 v61, v56, 2, v33
	ds_add_u32 v61, v188
	v_cndmask_b32_e32 v64, v154, v65, vcc
	v_lshl_add_u32 v155, v64, 2, v33
	ds_add_u32 v155, v188 offset:4096
	s_add_u32 s0, s0, 1
	s_cmp_ge_u32 s0, s13
	s_waitcnt lgkmcnt(4)
	s_barrier
	s_cbranch_scc1 .Lp1_drain1
.Lp1_c0:
	ds_read_b128 v[176:179], v99 offset:0
	ds_read_b128 v[180:183], v99 offset:4096
	ds_read_b128 v[230:233], v99 offset:1024
	ds_read_b128 v[234:237], v99 offset:5120
	ds_read_b128 v[238:241], v99 offset:2048
	ds_read_b128 v[242:245], v99 offset:6144
	ds_read_b128 v[246:249], v99 offset:3072
	ds_read_b128 v[50:53], v99 offset:7168
	v_max_i32_e32 v56, 0, v206
	v_max_i32_e32 v57, 0, v198
	v_max_i32_e32 v60, 0, v207
	v_max_i32_e32 v61, 0, v199
	v_max_i32_e32 v64, 0, v208
	v_max_i32_e32 v65, 0, v200
	v_max_i32_e32 v154, 0, v209
	v_max_i32_e32 v155, 0, v201
	v_mul_f32_e32 v156, v100, v56
	v_mul_f32_e32 v157, v101, v57
	s_waitcnt lgkmcnt(7)
	v_mfma_f32_32x32x16_bf16 v[0:15], v[34:37], v[176:179], 0
	v_fmac_f32_e32 v156, v102, v60
	v_fmac_f32_e32 v157, v103, v61
	v_fmac_f32_e32 v156, v104, v64
	v_fmac_f32_e32 v157, v105, v65
	v_fmac_f32_e32 v156, v106, v154
	v_fmac_f32_e32 v157, v107, v155
	v_max_i32_e32 v56, 0, v210
	v_max_i32_e32 v57, 0, v202
	v_max_i32_e32 v60, 0, v211
	v_max_i32_e32 v61, 0, v203
	v_max_i32_e32 v64, 0, v212
	s_waitcnt lgkmcnt(6)
	v_mfma_f32_32x32x16_bf16 v[160:175], v[34:37], v[180:183], 0
	s_waitcnt vmcnt(3)
	ds_write_b128 v140, v[16:19] offset:8192
	s_add_i32 s1, s0, 5
	s_min_i32 s1, s1, s14
	v_mad_i64_i32 v[184:185], s[2:3], s1, v193, v[116:117]
	global_load_dwordx4 v[16:19], v[184:185], off
	v_max_i32_e32 v65, 0, v204
	v_max_i32_e32 v154, 0, v213
	v_max_i32_e32 v155, 0, v205
	v_fmac_f32_e32 v156, v108, v56
	v_fmac_f32_e32 v157, v109, v57
	v_fmac_f32_e32 v156, v110, v60
	v_fmac_f32_e32 v157, v111, v61
	v_fmac_f32_e32 v156, v112, v64
	v_fmac_f32_e32 v157, v113, v65
	v_fmac_f32_e32 v156, v114, v154
	v_fmac_f32_e32 v157, v115, v155
	s_waitcnt lgkmcnt(6)
	v_mfma_f32_32x32x16_bf16 v[0:15], v[38:41], v[230:233], v[0:15]
	v_bfe_u32 v56, v157, 19, 12
	v_bfe_u32 v64, v156, 19, 12
	v_med3_u32 v56, v56, s94, v194
	v_med3_u32 v64, v64, s94, v194
	v_sub_u32_e32 v57, 0x86f, v56
	v_add_u32_e32 v60, 0xfffffb90, v56
	v_sub_u32_e32 v65, 0x86f, v64
	v_add_u32_e32 v154, 0xfffffb90, v64
	v_cmp_gt_f32_e32 vcc, 0, v157
	s_nop 1
	v_cndmask_b32_e32 v56, v60, v57, vcc
	s_waitcnt lgkmcnt(5)
	v_mfma_f32_32x32x16_bf16 v[160:175], v[38:41], v[234:237], v[160:175]
	v_cmp_gt_f32_e32 vcc, 0, v156
	v_lshl_add_u32 v61, v56, 2, v33
	ds_add_u32 v61, v188
	v_cndmask_b32_e32 v64, v154, v65, vcc
	v_lshl_add_u32 v155, v64, 2, v33
	ds_add_u32 v155, v188 offset:4096
	v_max_i32_e32 v56, 0, v222
	v_max_i32_e32 v57, 0, v214
	v_max_i32_e32 v60, 0, v223
	v_max_i32_e32 v61, 0, v215
	v_max_i32_e32 v64, 0, v224
	s_waitcnt lgkmcnt(6)
	v_mfma_f32_32x32x16_bf16 v[0:15], v[42:45], v[238:241], v[0:15]
	v_max_i32_e32 v65, 0, v216
	v_max_i32_e32 v154, 0, v225
	v_max_i32_e32 v155, 0, v217
	v_mul_f32_e32 v156, v100, v56
	v_mul_f32_e32 v157, v101, v57
	v_fmac_f32_e32 v156, v102, v60
	v_fmac_f32_e32 v157, v103, v61
	v_fmac_f32_e32 v156, v104, v64
	v_fmac_f32_e32 v157, v105, v65
	v_fmac_f32_e32 v156, v106, v154
	v_fmac_f32_e32 v157, v107, v155
	s_waitcnt lgkmcnt(5)
	v_mfma_f32_32x32x16_bf16 v[160:175], v[42:45], v[242:245], v[160:175]
	v_max_i32_e32 v56, 0, v226
	v_max_i32_e32 v57, 0, v218
	v_max_i32_e32 v60, 0, v227
	v_max_i32_e32 v61, 0, v219
	v_max_i32_e32 v64, 0, v228
	v_max_i32_e32 v65, 0, v220
	v_max_i32_e32 v154, 0, v229
	v_max_i32_e32 v155, 0, v221
	v_fmac_f32_e32 v156, v108, v56
	v_fmac_f32_e32 v157, v109, v57
	v_fmac_f32_e32 v156, v110, v60
	s_waitcnt lgkmcnt(4)
	v_mfma_f32_32x32x16_bf16 v[0:15], v[46:49], v[246:249], v[0:15]
	v_fmac_f32_e32 v157, v111, v61
	v_fmac_f32_e32 v156, v112, v64
	v_fmac_f32_e32 v157, v113, v65
	v_fmac_f32_e32 v156, v114, v154
	v_fmac_f32_e32 v157, v115, v155
	v_bfe_u32 v56, v157, 19, 12
	v_bfe_u32 v64, v156, 19, 12
	v_med3_u32 v56, v56, s94, v194
	v_med3_u32 v64, v64, s94, v194
	v_sub_u32_e32 v57, 0x86f, v56
	v_add_u32_e32 v60, 0xfffffb90, v56
	s_waitcnt lgkmcnt(3)
	v_mfma_f32_32x32x16_bf16 v[160:175], v[46:49], v[50:53], v[160:175]
	v_sub_u32_e32 v65, 0x86f, v64
	v_add_u32_e32 v154, 0xfffffb90, v64
	v_cmp_gt_f32_e32 vcc, 0, v157
	s_nop 1
	v_cndmask_b32_e32 v56, v60, v57, vcc
	v_cmp_gt_f32_e32 vcc, 0, v156
	v_lshl_add_u32 v61, v56, 2, v33
	ds_add_u32 v61, v188
	v_cndmask_b32_e32 v64, v154, v65, vcc
	v_lshl_add_u32 v155, v64, 2, v33
	ds_add_u32 v155, v188 offset:4096
	s_add_u32 s0, s0, 1
	s_cmp_ge_u32 s0, s13
	s_waitcnt lgkmcnt(4)
	s_barrier
	s_cbranch_scc1 .Lp1_drain0
	s_branch .Lp1_c1

.LBB0_1024:
	v_mov_b32_e32 v246, v149
	v_add_u32_e32 v247, 0x471, v246
	v_lshlrev_b32_e32 v247, 19, v247
	v_sub_u32_e32 v248, 0x86f, v246
	v_lshlrev_b32_e32 v248, 19, v248
	v_add_u32_e32 v248, 0x7fffffff, v248
	v_cmp_lt_i32_e32 vcc, 0x1ff, v246
	s_nop 1
	v_cndmask_b32_e32 v250, v248, v247, vcc
	v_cmp_ne_u32_e32 vcc, 0x1ff, v246
	s_nop 1
	v_cndmask_b32_e32 v250, 0, v250, vcc
	v_cmp_ne_u32_e32 vcc, 0x3ff, v246
	v_mov_b32_e32 v249, 0x7fc00000
	s_nop 0
	v_cndmask_b32_e32 v250, v249, v250, vcc
	v_cmp_le_i32_e32 vcc, 0, v246
	s_nop 1
	v_mov_b32_e32 v249, s33
	v_cndmask_b32_e32 v250, v249, v250, vcc
	v_add_u32_e32 v246, -1, v149
	v_add_u32_e32 v247, 0x471, v246
	v_lshlrev_b32_e32 v247, 19, v247
	v_sub_u32_e32 v248, 0x86f, v246
	v_lshlrev_b32_e32 v248, 19, v248
	v_add_u32_e32 v248, 0x7fffffff, v248
	v_cmp_lt_i32_e32 vcc, 0x1ff, v246
	s_nop 1
	v_cndmask_b32_e32 v156, v248, v247, vcc
	v_cmp_ne_u32_e32 vcc, 0x1ff, v246
	s_nop 1
	v_cndmask_b32_e32 v156, 0, v156, vcc
	v_cmp_ne_u32_e32 vcc, 0x3ff, v246
	v_mov_b32_e32 v249, 0x7fc00000
	s_nop 0
	v_cndmask_b32_e32 v156, v249, v156, vcc
	v_cmp_le_i32_e32 vcc, 0, v246
	s_nop 1
	v_mov_b32_e32 v249, s33
	v_cndmask_b32_e32 v156, v249, v156, vcc
	v_mov_b32_e32 v246, v159
	v_add_u32_e32 v247, 0x471, v246
	v_lshlrev_b32_e32 v247, 19, v247
	v_sub_u32_e32 v248, 0x86f, v246
	v_lshlrev_b32_e32 v248, 19, v248
	v_add_u32_e32 v248, 0x7fffffff, v248
	v_cmp_lt_i32_e32 vcc, 0x1ff, v246
	s_nop 1
	v_cndmask_b32_e32 v197, v248, v247, vcc
	v_cmp_ne_u32_e32 vcc, 0x1ff, v246
	s_nop 1
	v_cndmask_b32_e32 v197, 0, v197, vcc
	v_cmp_ne_u32_e32 vcc, 0x3ff, v246
	v_mov_b32_e32 v249, 0x7fc00000
	s_nop 0
	v_cndmask_b32_e32 v197, v249, v197, vcc
	v_cmp_le_i32_e32 vcc, 0, v246
	s_nop 1
	v_mov_b32_e32 v249, s33
	v_cndmask_b32_e32 v197, v249, v197, vcc
	v_add_u32_e32 v246, -1, v159
	v_add_u32_e32 v247, 0x471, v246
	v_lshlrev_b32_e32 v247, 19, v247
	v_sub_u32_e32 v248, 0x86f, v246
	v_lshlrev_b32_e32 v248, 19, v248
	v_add_u32_e32 v248, 0x7fffffff, v248
	v_cmp_lt_i32_e32 vcc, 0x1ff, v246
	s_nop 1
	v_cndmask_b32_e32 v157, v248, v247, vcc
	v_cmp_ne_u32_e32 vcc, 0x1ff, v246
	s_nop 1
	v_cndmask_b32_e32 v157, 0, v157, vcc
	v_cmp_ne_u32_e32 vcc, 0x3ff, v246
	v_mov_b32_e32 v249, 0x7fc00000
	s_nop 0
	v_cndmask_b32_e32 v157, v249, v157, vcc
	v_cmp_le_i32_e32 vcc, 0, v246
	s_nop 1
	v_mov_b32_e32 v249, s33
	v_cndmask_b32_e32 v157, v249, v157, vcc
	v_readlane_b32 s4, v162, 0
	v_readlane_b32 s5, v162, 32
	v_and_b32_e32 v246, 1, v196
	v_lshlrev_b32_e32 v246, 2, v246
	v_bfe_u32 v247, v196, 1, 1
	v_lshl_add_u32 v246, v247, 10, v246
	v_mov_b32_e32 v247, s5
	v_mov_b32_e32 v248, s4
	v_and_b32_e32 v249, 4, v196
	v_cmp_ne_u32_e32 vcc, 0, v249
	s_nop 1
	v_cndmask_b32_e32 v248, v248, v247, vcc
	v_add_u32_e32 v162, v248, v246
	v_lshlrev_b32_e32 v246, 2, v196
	v_add_u32_e32 v246, 0x800, v246
	v_add_u32_e32 v246, v247, v246
	v_cmp_lt_u32_e32 vcc, 7, v196
	s_nop 1
	v_cndmask_b32_e32 v162, v162, v246, vcc
	ds_read_b128 v[164:167], v99 offset:0
	ds_read_b128 v[168:171], v99 offset:4096
	ds_read_b128 v[172:175], v99 offset:1024
	ds_read_b128 v[176:179], v99 offset:5120
	ds_read_b128 v[230:233], v99 offset:2048
	ds_read_b128 v[234:237], v99 offset:6144
	ds_read_b128 v[238:241], v99 offset:3072
	ds_read_b128 v[242:245], v99 offset:7168
	s_waitcnt lgkmcnt(7)
	v_mfma_f32_32x32x16_bf16 v[16:31], v[34:37], v[164:167], 0
	s_waitcnt lgkmcnt(6)
	v_mfma_f32_32x32x16_bf16 v[0:15], v[34:37], v[168:171], 0
	s_waitcnt vmcnt(3)
	ds_write_b128 v140, v[50:53] offset:8192
	s_add_i32 s4, s18, 5
	s_min_i32 s4, s4, s14
	v_mad_i64_i32 v[164:165], s[4:5], s4, v193, v[116:117]
	global_load_dwordx4 v[50:53], v[164:165], off
	s_waitcnt lgkmcnt(6)
	v_mfma_f32_32x32x16_bf16 v[16:31], v[38:41], v[172:175], v[16:31]
	s_waitcnt lgkmcnt(5)
	v_mfma_f32_32x32x16_bf16 v[0:15], v[38:41], v[176:179], v[0:15]
	s_waitcnt lgkmcnt(4)
	v_mfma_f32_32x32x16_bf16 v[16:31], v[42:45], v[230:233], v[16:31]
	s_waitcnt lgkmcnt(3)
	v_mfma_f32_32x32x16_bf16 v[0:15], v[42:45], v[234:237], v[0:15]
	s_waitcnt lgkmcnt(2)
	v_mfma_f32_32x32x16_bf16 v[16:31], v[46:49], v[238:241], v[16:31]
	s_waitcnt lgkmcnt(1)
	v_mfma_f32_32x32x16_bf16 v[0:15], v[46:49], v[242:245], v[0:15]
	s_add_u32 s18, s18, 1
	s_cmp_ge_u32 s18, s13
	s_waitcnt lgkmcnt(0)
	s_barrier
	s_cbranch_scc1 .Lp2_drain0

.Lp2_skip4:
	ds_write_b32 v162, v33
	v_add_u32_e32 v162, 8, v162
	s_add_u32 s18, s18, 1
	s_cmp_ge_u32 s18, s13
	s_waitcnt lgkmcnt(1)
	s_barrier
	s_cbranch_scc1 .Lp2_drain1

.Lp2_skip16:
	ds_write_b32 v162, v33
	v_add_u32_e32 v162, 8, v162
	s_add_u32 s0, s0, 0xffffff00
	s_addc_u32 s1, s1, -1
	s_add_u32 s18, s18, 1
	s_cmp_ge_u32 s18, s13
	s_waitcnt lgkmcnt(1)
	s_barrier
	s_cbranch_scc1 .Lp2_drain0
	s_branch .Lp2_c1
